# hand-scheduled SwiGLU epilogue (fewer VALU, no hazard nops), unit-header tile decode without integer division, SALU has-next compare
# speedup vs baseline: 1.0326x; 1.0120x over previous
;     __host__ __device__ bool next(int i, Unit& u) const {
;         const long L = (long)i * G + c; if (L >= nwg) return false;
;         int wgid = (int)L; { const int q = nwg / NXCD, r = nwg % NXCD, xcd = wgid % NXCD, off = wgid / NXCD; wgid = (xcd < r ? xcd * (q + 1) : r * (q + 1) + (xcd - r) * q) + off; }
;         const int nig = WGM * nN, gid = wgid / nig, fm = gid * WGM, gsz = (nM - fm) < WGM ? (nM - fm) : WGM;
;         u.pm = fm + ((wgid % nig) % gsz); u.pn = (wgid % nig) / gsz; return true;
.LBB0_121:
	s_add_i32 s63, s65, 1
	s_mul_i32 s30, s63, s9
	s_mul_hi_u32 s31, s63, s90
	s_add_i32 s31, s31, s30
	s_mul_i32 s30, s63, s90
	s_add_u32 s30, s30, s19
	s_addc_u32 s31, s31, s36
	s_waitcnt lgkmcnt(0)
	s_cmp_lt_u32 s30, 0x600
	s_cselect_b64 s[38:39], -1, 0
	s_cbranch_scc0 .LBB0_123
	s_ashr_i32 s31, s30, 31
	s_lshr_b32 s31, s31, 29
	s_add_i32 s31, s30, s31
	s_ashr_i32 s34, s31, 3
	s_and_b32 s31, s31, -8
	s_sub_i32 s30, s30, s31
	s_cmp_lt_i32 s30, 0
	s_movk_i32 s31, 0xc1
	s_cselect_b32 s31, s31, 0xc0
	s_mul_i32 s30, s30, s31
	s_add_i32 s30, s30, s34
	s_mul_hi_i32 s31, s30, 0x2aaaaaab
	s_lshr_b32 s34, s31, 31
	s_ashr_i32 s31, s31, 4
	s_add_i32 s31, s31, s34
	s_lshl_b32 s34, s31, 3
	s_mulk_i32 s31, 0x60
	s_sub_i32 s30, s30, s31
	s_ashr_i32 s48, s30, 3
	s_and_b32 s30, s30, 7
	s_add_i32 s50, s34, s30

;     __host__ __device__ bool next(int i, Unit& u) const {
;         const long L = (long)i * G + c; if (L >= nwg) return false;
;         int wgid = (int)L; { const int q = nwg / NXCD, r = nwg % NXCD, xcd = wgid % NXCD, off = wgid / NXCD; wgid = (xcd < r ? xcd * (q + 1) : r * (q + 1) + (xcd - r) * q) + off; }
.LBB0_149:
	s_add_i32 s62, s64, 1
	s_mul_i32 s30, s62, s9
	s_mul_hi_u32 s31, s62, s90
	s_add_i32 s31, s31, s30
	s_mul_i32 s30, s62, s90
	s_add_u32 s30, s30, s19
	s_addc_u32 s31, s31, s36
	s_waitcnt lgkmcnt(0)
	s_cmp_lt_u32 s30, 0x400
	s_cselect_b64 s[42:43], -1, 0
	s_cbranch_scc0 .LBB0_155
	s_ashr_i32 s31, s30, 31
	s_lshr_b32 s31, s31, 29
	s_add_i32 s34, s30, s31
	s_and_b32 s31, s34, -8
	s_sub_i32 s35, s30, s31
	s_cmp_gt_i32 s35, -1
	s_mov_b64 s[30:31], -1
	s_cbranch_scc0 .LBB0_152
	s_lshl_b32 s40, s35, 7
	s_mov_b64 s[30:31], 0

;     __host__ __device__ bool next(int i, Unit& u) const {
;     ...
;         const int nig = WGM * nN, gid = wgid / nig, fm = gid * WGM, gsz = (nM - fm) < WGM ? (nM - fm) : WGM;
;         u.pm = fm + ((wgid % nig) % gsz); u.pn = (wgid % nig) / gsz; return true;
.LBB0_154:
	s_ashr_i32 s30, s34, 3
	s_add_i32 s30, s40, s30
	s_ashr_i32 s31, s30, 31
	s_lshr_b32 s31, s31, 26
	s_add_i32 s31, s30, s31
	s_ashr_i32 s34, s31, 6
	s_lshl_b32 s34, s34, 3
	s_andn2_b32 s31, s31, 63
	s_sub_i32 s30, s30, s31
	s_ashr_i32 s48, s30, 3
	s_and_b32 s30, s30, 7
	s_add_i32 s50, s34, s30

;     __host__ __device__ bool next(int i, Unit& u) const {
;         const long L = (long)i * G + c; if (L >= nwg) return false;
;         int wgid = (int)L; { const int q = nwg / NXCD, r = nwg % NXCD, xcd = wgid % NXCD, off = wgid / NXCD; wgid = (xcd < r ? xcd * (q + 1) : r * (q + 1) + (xcd - r) * q) + off; }
.LBB0_182:
	s_add_i32 s23, s2, 1
	s_mul_i32 s30, s23, s9
	s_mul_hi_u32 s31, s23, s90
	s_add_i32 s31, s31, s30
	s_mul_i32 s30, s23, s90
	s_add_u32 s30, s30, s19
	s_addc_u32 s31, s31, s65
	s_cmp_lt_u32 s30, 0x200
	s_cselect_b64 s[42:43], -1, 0
	s_cbranch_scc0 .LBB0_188
	s_ashr_i32 s31, s30, 31
	s_lshr_b32 s31, s31, 29
	s_add_i32 s40, s30, s31
	s_and_b32 s31, s40, -8
	s_sub_i32 s41, s30, s31
	s_cmp_gt_i32 s41, -1
	s_mov_b64 s[30:31], -1
	s_cbranch_scc0 .LBB0_185
	s_lshl_b32 s54, s41, 6
	s_mov_b64 s[30:31], 0

;     __host__ __device__ bool next(int i, Unit& u) const {
;     ...
;         const int nig = WGM * nN, gid = wgid / nig, fm = gid * WGM, gsz = (nM - fm) < WGM ? (nM - fm) : WGM;
;         u.pm = fm + ((wgid % nig) % gsz); u.pn = (wgid % nig) / gsz; return true;
.LBB0_187:
	s_ashr_i32 s30, s40, 3
	s_add_i32 s30, s54, s30
	s_ashr_i32 s31, s30, 31
	s_lshr_b32 s31, s31, 27
	s_add_i32 s31, s30, s31
	s_ashr_i32 s40, s31, 5
	s_lshl_b32 s40, s40, 3
	s_andn2_b32 s31, s31, 31
	s_sub_i32 s30, s30, s31
	s_ashr_i32 s66, s30, 3
	s_and_b32 s30, s30, 7
	s_add_i32 s67, s40, s30

;     __host__ __device__ bool next(int i, Unit& u) const {
;         const long L = (long)i * G + c; if (L >= nwg) return false;
;         int wgid = (int)L; { const int q = nwg / NXCD, r = nwg % NXCD, xcd = wgid % NXCD, off = wgid / NXCD; wgid = (xcd < r ? xcd * (q + 1) : r * (q + 1) + (xcd - r) * q) + off; }
;         const int nig = WGM * nN, gid = wgid / nig, fm = gid * WGM, gsz = (nM - fm) < WGM ? (nM - fm) : WGM;
;         u.pm = fm + ((wgid % nig) % gsz); u.pn = (wgid % nig) / gsz; return true;
.LBB0_233:
	s_add_i32 s57, s58, 1
	s_mul_i32 s25, s57, s9
	s_mul_hi_u32 s27, s57, s90
	s_add_i32 s27, s27, s25
	s_mul_i32 s25, s57, s90
	s_add_u32 s34, s25, s19
	s_addc_u32 s35, s27, s36
	s_cmp_lt_u32 s34, 0xb00
	s_cselect_b64 s[42:43], -1, 0
	s_cbranch_scc0 .LBB0_235
	s_ashr_i32 s24, s34, 31
	s_lshr_b32 s24, s24, 29
	s_add_i32 s24, s34, s24
	s_ashr_i32 s25, s24, 3
	s_and_b32 s24, s24, -8
	s_sub_i32 s24, s34, s24
	s_cmp_lt_i32 s24, 0
	s_movk_i32 s26, 0x161
	s_cselect_b32 s26, s26, 0x160
	s_mul_i32 s24, s24, s26
	s_add_i32 s24, s24, s25
	s_mul_hi_i32 s25, s24, 0x2e8ba2e9
	s_lshr_b32 s26, s25, 31
	s_ashr_i32 s25, s25, 5
	s_add_i32 s25, s25, s26
	s_lshl_b32 s26, s25, 3
	s_mulk_i32 s25, 0xb0
	s_sub_i32 s25, s24, s25
	s_ashr_i32 s24, s25, 3
	s_and_b32 s25, s25, 7
	s_add_i32 s26, s26, s25

; __device__ __forceinline__ unsigned cvt_pk_bf16(float lo, float hi) { unsigned r; asm volatile("v_cvt_pk_bf16_f32 %0, %1, %2" : "=v"(r) : "v"(lo), "v"(hi)); return r; }
;     __device__ __forceinline__ void operator()(const f32x4 (&acc)[2][2][4][2], const Unit& u, int wr, int wc, int fr, int fq, LAS unsigned char* lds, int tid, int ui, const Unit& nxt, bool has_next) const {
;     ...
;         const int row0 = u.pm * 256 + wr * 64 + fr, col0 = u.pn * 128 + wc * 32 + 8 * fq;
;         float rsv[2][4]; rs_read(lds, ui & 1, wr, fr, rsv);
; #pragma unroll
;         for (int ai = 0; ai < 2; ++ai)
; #pragma unroll
;             for (int m = 0; m < 4; ++m) {
;                 const int row = row0 + ai * 128 + m * 16;
;                 const float rs = rsv[ai][m];
;                 typedef float f32x2 __attribute__((ext_vector_type(2)));
;                 const f32x2 rs2 = (f32x2){rs, rs}, nrs2 = (f32x2){-LOG2E * rs, -LOG2E * rs};
;                 unsigned wv[4];
; #pragma unroll
;                 for (int n = 0; n < 2; ++n)
; #pragma unroll
;                     for (int hp = 0; hp < 2; ++hp) {
;                         const f32x2 ag = (f32x2){acc[ai][0][m][n][2 * hp], acc[ai][0][m][n][2 * hp + 1]}, au = (f32x2){acc[ai][1][m][n][2 * hp], acc[ai][1][m][n][2 * hp + 1]};
;                         const f32x2 g = ag * rs2, up = au * rs2, ne = ag * nrs2;
;                         const f32x2 dd = (f32x2){__builtin_amdgcn_exp2f(ne.x), __builtin_amdgcn_exp2f(ne.y)} + 1.0f;
;                         const f32x2 rr = (f32x2){__builtin_amdgcn_rcpf(dd.x), __builtin_amdgcn_rcpf(dd.y)};
;                         const f32x2 oo = (g * rr) * up;
;                         wv[n * 2 + hp] = cvt_pk_bf16(oo.x, oo.y);
;                     }
;                 u32x4 w; w.x = wv[0]; w.y = wv[1]; w.z = wv[2]; w.w = wv[3];
;                 __builtin_nontemporal_store(w, (u32x4*)(O + (size_t)row * FF + col0));
.LBB0_241:
	s_lshl_b32 s4, s58, 10
	s_and_b32 s25, s4, 0x400
	v_add_u32_e32 v148, s25, v163
	ds_read2_b32 v[156:157], v148 offset1:16
	ds_read2_b32 v[152:153], v148 offset0:32 offset1:48
	ds_read2_b32 v[150:151], v148 offset0:128 offset1:144
	ds_read2_b32 v[148:149], v148 offset0:160 offset1:176
	v_lshl_or_b32 v154, s30, 7, v164
	s_waitcnt lgkmcnt(0)
	v_lshl_add_u32 v166, s28, 8, v160
	v_ashrrev_i32_e32 v155, 31, v154
	v_mov_b64_e32 v[186:187], s[16:17]
	v_lshlrev_b64 v[188:189], 1, v[154:155]
	v_mul_f32_e32 v170, 0xbfb8aa3b, v156
	v_mul_f32_e32 v172, v156, v156
	v_add_u32_e32 v167, 0, v166
	v_rcp_f32_e32 v172, v172
	v_mad_i64_i32 v[174:175], s[4:5], v167, s6, v[186:187]
	v_lshl_add_u64 v[174:175], v[174:175], 0, v[188:189]
	v_pk_mul_f32 v[128:129], v[132:133], v[128:129]
	v_pk_mul_f32 v[132:133], v[132:133], v[170:171] op_sel_hi:[1,0]
	v_pk_mul_f32 v[130:131], v[134:135], v[130:131]
	v_pk_mul_f32 v[134:135], v[134:135], v[170:171] op_sel_hi:[1,0]
	v_exp_f32_e32 v132, v132
	v_exp_f32_e32 v133, v133
	v_exp_f32_e32 v134, v134
	v_exp_f32_e32 v135, v135
	v_pk_fma_f32 v[132:133], v[132:133], v[172:173], v[172:173] op_sel_hi:[1,0,0]
	v_pk_fma_f32 v[134:135], v[134:135], v[172:173], v[172:173] op_sel_hi:[1,0,0]
	v_rcp_f32_e32 v132, v132
	v_rcp_f32_e32 v133, v133
	v_rcp_f32_e32 v134, v134
	v_rcp_f32_e32 v135, v135
	v_pk_mul_f32 v[128:129], v[128:129], v[132:133]
	v_pk_mul_f32 v[130:131], v[130:131], v[134:135]
	v_cvt_pk_bf16_f32 v132, v128, v129
	v_cvt_pk_bf16_f32 v133, v130, v131
	v_pk_mul_f32 v[120:121], v[124:125], v[120:121]
	v_pk_mul_f32 v[124:125], v[124:125], v[170:171] op_sel_hi:[1,0]
	v_pk_mul_f32 v[122:123], v[126:127], v[122:123]
	v_pk_mul_f32 v[126:127], v[126:127], v[170:171] op_sel_hi:[1,0]
	v_exp_f32_e32 v124, v124
	v_exp_f32_e32 v125, v125
	v_exp_f32_e32 v126, v126
	v_exp_f32_e32 v127, v127
	v_pk_fma_f32 v[124:125], v[124:125], v[172:173], v[172:173] op_sel_hi:[1,0,0]
	v_pk_fma_f32 v[126:127], v[126:127], v[172:173], v[172:173] op_sel_hi:[1,0,0]
	v_rcp_f32_e32 v124, v124
	v_rcp_f32_e32 v125, v125
	v_rcp_f32_e32 v126, v126
	v_rcp_f32_e32 v127, v127
	v_pk_mul_f32 v[120:121], v[120:121], v[124:125]
	v_pk_mul_f32 v[122:123], v[122:123], v[126:127]
	v_cvt_pk_bf16_f32 v134, v120, v121
	v_cvt_pk_bf16_f32 v135, v122, v123
	global_store_dwordx4 v[174:175], v[132:135], off nt
	s_cmp_eq_u64 s[22:23], 0
	s_cbranch_scc1 .Lmy_epibar_swiglu
	s_barrier
.Lmy_epibar_swiglu:
	v_mul_f32_e32 v170, 0xbfb8aa3b, v157
	v_mul_f32_e32 v172, v157, v157
	v_add_u32_e32 v167, 16, v166
	v_rcp_f32_e32 v172, v172
	v_mad_i64_i32 v[174:175], s[4:5], v167, s6, v[186:187]
	v_lshl_add_u64 v[174:175], v[174:175], 0, v[188:189]
	v_pk_mul_f32 v[112:113], v[116:117], v[112:113]
	v_pk_mul_f32 v[116:117], v[116:117], v[170:171] op_sel_hi:[1,0]
	v_pk_mul_f32 v[114:115], v[118:119], v[114:115]
	v_pk_mul_f32 v[118:119], v[118:119], v[170:171] op_sel_hi:[1,0]
	v_exp_f32_e32 v116, v116
	v_exp_f32_e32 v117, v117
	v_exp_f32_e32 v118, v118
	v_exp_f32_e32 v119, v119
	v_pk_fma_f32 v[116:117], v[116:117], v[172:173], v[172:173] op_sel_hi:[1,0,0]
	v_pk_fma_f32 v[118:119], v[118:119], v[172:173], v[172:173] op_sel_hi:[1,0,0]
	v_rcp_f32_e32 v116, v116
	v_rcp_f32_e32 v117, v117
	v_rcp_f32_e32 v118, v118
	v_rcp_f32_e32 v119, v119
	v_pk_mul_f32 v[112:113], v[112:113], v[116:117]
	v_pk_mul_f32 v[114:115], v[114:115], v[118:119]
	v_cvt_pk_bf16_f32 v116, v112, v113
	v_cvt_pk_bf16_f32 v117, v114, v115
	v_pk_mul_f32 v[104:105], v[108:109], v[104:105]
	v_pk_mul_f32 v[108:109], v[108:109], v[170:171] op_sel_hi:[1,0]
	v_pk_mul_f32 v[106:107], v[110:111], v[106:107]
	v_pk_mul_f32 v[110:111], v[110:111], v[170:171] op_sel_hi:[1,0]
	v_exp_f32_e32 v108, v108
	v_exp_f32_e32 v109, v109
	v_exp_f32_e32 v110, v110
	v_exp_f32_e32 v111, v111
	v_pk_fma_f32 v[108:109], v[108:109], v[172:173], v[172:173] op_sel_hi:[1,0,0]
	v_pk_fma_f32 v[110:111], v[110:111], v[172:173], v[172:173] op_sel_hi:[1,0,0]
	v_rcp_f32_e32 v108, v108
	v_rcp_f32_e32 v109, v109
	v_rcp_f32_e32 v110, v110
	v_rcp_f32_e32 v111, v111
	v_pk_mul_f32 v[104:105], v[104:105], v[108:109]
	v_pk_mul_f32 v[106:107], v[106:107], v[110:111]
	v_cvt_pk_bf16_f32 v118, v104, v105
	v_cvt_pk_bf16_f32 v119, v106, v107
	global_store_dwordx4 v[174:175], v[116:119], off nt
	v_mul_f32_e32 v170, 0xbfb8aa3b, v152
	v_mul_f32_e32 v172, v152, v152
	v_add_u32_e32 v167, 32, v166
	v_rcp_f32_e32 v172, v172
	v_mad_i64_i32 v[174:175], s[4:5], v167, s6, v[186:187]
	v_lshl_add_u64 v[174:175], v[174:175], 0, v[188:189]
	v_pk_mul_f32 v[96:97], v[100:101], v[96:97]
	v_pk_mul_f32 v[100:101], v[100:101], v[170:171] op_sel_hi:[1,0]
	v_pk_mul_f32 v[98:99], v[102:103], v[98:99]
	v_pk_mul_f32 v[102:103], v[102:103], v[170:171] op_sel_hi:[1,0]
	v_exp_f32_e32 v100, v100
	v_exp_f32_e32 v101, v101
	v_exp_f32_e32 v102, v102
	v_exp_f32_e32 v103, v103
	v_pk_fma_f32 v[100:101], v[100:101], v[172:173], v[172:173] op_sel_hi:[1,0,0]
	v_pk_fma_f32 v[102:103], v[102:103], v[172:173], v[172:173] op_sel_hi:[1,0,0]
	v_rcp_f32_e32 v100, v100
	v_rcp_f32_e32 v101, v101
	v_rcp_f32_e32 v102, v102
	v_rcp_f32_e32 v103, v103
	v_pk_mul_f32 v[96:97], v[96:97], v[100:101]
	v_pk_mul_f32 v[98:99], v[98:99], v[102:103]
	v_cvt_pk_bf16_f32 v100, v96, v97
	v_cvt_pk_bf16_f32 v101, v98, v99
	v_pk_mul_f32 v[88:89], v[92:93], v[88:89]
	v_pk_mul_f32 v[92:93], v[92:93], v[170:171] op_sel_hi:[1,0]
	v_pk_mul_f32 v[90:91], v[94:95], v[90:91]
	v_pk_mul_f32 v[94:95], v[94:95], v[170:171] op_sel_hi:[1,0]
	v_exp_f32_e32 v92, v92
	v_exp_f32_e32 v93, v93
	v_exp_f32_e32 v94, v94
	v_exp_f32_e32 v95, v95
	v_pk_fma_f32 v[92:93], v[92:93], v[172:173], v[172:173] op_sel_hi:[1,0,0]
	v_pk_fma_f32 v[94:95], v[94:95], v[172:173], v[172:173] op_sel_hi:[1,0,0]
; __device__ __forceinline__ unsigned cvt_pk_bf16(float lo, float hi) { unsigned r; asm volatile("v_cvt_pk_bf16_f32 %0, %1, %2" : "=v"(r) : "v"(lo), "v"(hi)); return r; }
;     __device__ __forceinline__ void operator()(const f32x4 (&acc)[2][2][4][2], const Unit& u, int wr, int wc, int fr, int fq, LAS unsigned char* lds, int tid, int ui, const Unit& nxt, bool has_next) const {
;     ...
; #pragma unroll
;                 for (int n = 0; n < 2; ++n)
; #pragma unroll
;                     for (int hp = 0; hp < 2; ++hp) {
;                         const f32x2 ag = (f32x2){acc[ai][0][m][n][2 * hp], acc[ai][0][m][n][2 * hp + 1]}, au = (f32x2){acc[ai][1][m][n][2 * hp], acc[ai][1][m][n][2 * hp + 1]};
;                         const f32x2 g = ag * rs2, up = au * rs2, ne = ag * nrs2;
;                         const f32x2 dd = (f32x2){__builtin_amdgcn_exp2f(ne.x), __builtin_amdgcn_exp2f(ne.y)} + 1.0f;
;                         const f32x2 rr = (f32x2){__builtin_amdgcn_rcpf(dd.x), __builtin_amdgcn_rcpf(dd.y)};
;                         const f32x2 oo = (g * rr) * up;
;                         wv[n * 2 + hp] = cvt_pk_bf16(oo.x, oo.y);
;                     }
;                 u32x4 w; w.x = wv[0]; w.y = wv[1]; w.z = wv[2]; w.w = wv[3];
;                 __builtin_nontemporal_store(w, (u32x4*)(O + (size_t)row * FF + col0));
	v_rcp_f32_e32 v92, v92
	v_rcp_f32_e32 v93, v93
	v_rcp_f32_e32 v94, v94
	v_rcp_f32_e32 v95, v95
	v_pk_mul_f32 v[88:89], v[88:89], v[92:93]
	v_pk_mul_f32 v[90:91], v[90:91], v[94:95]
	v_cvt_pk_bf16_f32 v102, v88, v89
	v_cvt_pk_bf16_f32 v103, v90, v91
	global_store_dwordx4 v[174:175], v[100:103], off nt
	v_mul_f32_e32 v170, 0xbfb8aa3b, v153
	v_mul_f32_e32 v172, v153, v153
	v_add_u32_e32 v167, 48, v166
	v_rcp_f32_e32 v172, v172
	v_mad_i64_i32 v[174:175], s[4:5], v167, s6, v[186:187]
	v_lshl_add_u64 v[174:175], v[174:175], 0, v[188:189]
	v_pk_mul_f32 v[80:81], v[84:85], v[80:81]
	v_pk_mul_f32 v[84:85], v[84:85], v[170:171] op_sel_hi:[1,0]
	v_pk_mul_f32 v[82:83], v[86:87], v[82:83]
	v_pk_mul_f32 v[86:87], v[86:87], v[170:171] op_sel_hi:[1,0]
	v_exp_f32_e32 v84, v84
	v_exp_f32_e32 v85, v85
	v_exp_f32_e32 v86, v86
	v_exp_f32_e32 v87, v87
	v_pk_fma_f32 v[84:85], v[84:85], v[172:173], v[172:173] op_sel_hi:[1,0,0]
	v_pk_fma_f32 v[86:87], v[86:87], v[172:173], v[172:173] op_sel_hi:[1,0,0]
	v_rcp_f32_e32 v84, v84
	v_rcp_f32_e32 v85, v85
	v_rcp_f32_e32 v86, v86
	v_rcp_f32_e32 v87, v87
	v_pk_mul_f32 v[80:81], v[80:81], v[84:85]
	v_pk_mul_f32 v[82:83], v[82:83], v[86:87]
	v_cvt_pk_bf16_f32 v84, v80, v81
	v_cvt_pk_bf16_f32 v85, v82, v83
	v_pk_mul_f32 v[72:73], v[76:77], v[72:73]
	v_pk_mul_f32 v[76:77], v[76:77], v[170:171] op_sel_hi:[1,0]
	v_pk_mul_f32 v[74:75], v[78:79], v[74:75]
	v_pk_mul_f32 v[78:79], v[78:79], v[170:171] op_sel_hi:[1,0]
	v_exp_f32_e32 v76, v76
	v_exp_f32_e32 v77, v77
	v_exp_f32_e32 v78, v78
	v_exp_f32_e32 v79, v79
	v_pk_fma_f32 v[76:77], v[76:77], v[172:173], v[172:173] op_sel_hi:[1,0,0]
	v_pk_fma_f32 v[78:79], v[78:79], v[172:173], v[172:173] op_sel_hi:[1,0,0]
	v_rcp_f32_e32 v76, v76
	v_rcp_f32_e32 v77, v77
	v_rcp_f32_e32 v78, v78
	v_rcp_f32_e32 v79, v79
	v_pk_mul_f32 v[72:73], v[72:73], v[76:77]
	v_pk_mul_f32 v[74:75], v[74:75], v[78:79]
	v_cvt_pk_bf16_f32 v86, v72, v73
	v_cvt_pk_bf16_f32 v87, v74, v75
	global_store_dwordx4 v[174:175], v[84:87], off nt
	v_mul_f32_e32 v170, 0xbfb8aa3b, v150
	v_mul_f32_e32 v172, v150, v150
	v_add_u32_e32 v167, 128, v166
	v_rcp_f32_e32 v172, v172
	v_mad_i64_i32 v[174:175], s[4:5], v167, s6, v[186:187]
	v_lshl_add_u64 v[174:175], v[174:175], 0, v[188:189]
	v_pk_mul_f32 v[64:65], v[68:69], v[64:65]
	v_pk_mul_f32 v[68:69], v[68:69], v[170:171] op_sel_hi:[1,0]
	v_pk_mul_f32 v[66:67], v[70:71], v[66:67]
	v_pk_mul_f32 v[70:71], v[70:71], v[170:171] op_sel_hi:[1,0]
	v_exp_f32_e32 v68, v68
	v_exp_f32_e32 v69, v69
	v_exp_f32_e32 v70, v70
	v_exp_f32_e32 v71, v71
	v_pk_fma_f32 v[68:69], v[68:69], v[172:173], v[172:173] op_sel_hi:[1,0,0]
	v_pk_fma_f32 v[70:71], v[70:71], v[172:173], v[172:173] op_sel_hi:[1,0,0]
	v_rcp_f32_e32 v68, v68
	v_rcp_f32_e32 v69, v69
	v_rcp_f32_e32 v70, v70
	v_rcp_f32_e32 v71, v71
	v_pk_mul_f32 v[64:65], v[64:65], v[68:69]
	v_pk_mul_f32 v[66:67], v[66:67], v[70:71]
	v_cvt_pk_bf16_f32 v68, v64, v65
	v_cvt_pk_bf16_f32 v69, v66, v67
	v_pk_mul_f32 v[48:49], v[52:53], v[48:49]
	v_pk_mul_f32 v[52:53], v[52:53], v[170:171] op_sel_hi:[1,0]
	v_pk_mul_f32 v[50:51], v[54:55], v[50:51]
	v_pk_mul_f32 v[54:55], v[54:55], v[170:171] op_sel_hi:[1,0]
	v_exp_f32_e32 v52, v52
	v_exp_f32_e32 v53, v53
	v_exp_f32_e32 v54, v54
	v_exp_f32_e32 v55, v55
	v_pk_fma_f32 v[52:53], v[52:53], v[172:173], v[172:173] op_sel_hi:[1,0,0]
	v_pk_fma_f32 v[54:55], v[54:55], v[172:173], v[172:173] op_sel_hi:[1,0,0]
	v_rcp_f32_e32 v52, v52
	v_rcp_f32_e32 v53, v53
	v_rcp_f32_e32 v54, v54
	v_rcp_f32_e32 v55, v55
	v_pk_mul_f32 v[48:49], v[48:49], v[52:53]
	v_pk_mul_f32 v[50:51], v[50:51], v[54:55]
	v_cvt_pk_bf16_f32 v70, v48, v49
	v_cvt_pk_bf16_f32 v71, v50, v51
	global_store_dwordx4 v[174:175], v[68:71], off nt
	v_mul_f32_e32 v170, 0xbfb8aa3b, v151
	v_mul_f32_e32 v172, v151, v151
	v_add_u32_e32 v167, 144, v166
	v_rcp_f32_e32 v172, v172
	v_mad_i64_i32 v[174:175], s[4:5], v167, s6, v[186:187]
	v_lshl_add_u64 v[174:175], v[174:175], 0, v[188:189]
	v_pk_mul_f32 v[40:41], v[44:45], v[40:41]
	v_pk_mul_f32 v[44:45], v[44:45], v[170:171] op_sel_hi:[1,0]
	v_pk_mul_f32 v[42:43], v[46:47], v[42:43]
	v_pk_mul_f32 v[46:47], v[46:47], v[170:171] op_sel_hi:[1,0]
	v_exp_f32_e32 v44, v44
	v_exp_f32_e32 v45, v45
	v_exp_f32_e32 v46, v46
	v_exp_f32_e32 v47, v47
	v_pk_fma_f32 v[44:45], v[44:45], v[172:173], v[172:173] op_sel_hi:[1,0,0]
	v_pk_fma_f32 v[46:47], v[46:47], v[172:173], v[172:173] op_sel_hi:[1,0,0]
	v_rcp_f32_e32 v44, v44
	v_rcp_f32_e32 v45, v45
	v_rcp_f32_e32 v46, v46
	v_rcp_f32_e32 v47, v47
	v_pk_mul_f32 v[40:41], v[40:41], v[44:45]
	v_pk_mul_f32 v[42:43], v[42:43], v[46:47]
	v_cvt_pk_bf16_f32 v44, v40, v41
	v_cvt_pk_bf16_f32 v45, v42, v43
	v_pk_mul_f32 v[32:33], v[36:37], v[32:33]
	v_pk_mul_f32 v[36:37], v[36:37], v[170:171] op_sel_hi:[1,0]
; __device__ __forceinline__ unsigned cvt_pk_bf16(float lo, float hi) { unsigned r; asm volatile("v_cvt_pk_bf16_f32 %0, %1, %2" : "=v"(r) : "v"(lo), "v"(hi)); return r; }
; #define LAS __attribute__((address_space(3)))
; __device__ __forceinline__ void rs_finish(LAS unsigned char* lds, int buf, int tid, const f32x4& a, const f32x4& b) {
;     float t = ((a.x + a.y) + (a.z + a.w)) + ((b.x + b.y) + (b.z + b.w)); t += __shfl_xor(t, 1);
;     if (!(tid & 1)) ((LAS float*)(lds + RS_LDS_OFF))[buf * 256 + (tid >> 1)] = rsqrtf(t * (1.f / D) + RMS_EPS);
;     __device__ __forceinline__ void operator()(const f32x4 (&acc)[2][2][4][2], const Unit& u, int wr, int wc, int fr, int fq, LAS unsigned char* lds, int tid, int ui, const Unit& nxt, bool has_next) const {
;     ...
; #pragma unroll
;                 for (int n = 0; n < 2; ++n)
; #pragma unroll
;                     for (int hp = 0; hp < 2; ++hp) {
;                         const f32x2 ag = (f32x2){acc[ai][0][m][n][2 * hp], acc[ai][0][m][n][2 * hp + 1]}, au = (f32x2){acc[ai][1][m][n][2 * hp], acc[ai][1][m][n][2 * hp + 1]};
;                         const f32x2 g = ag * rs2, up = au * rs2, ne = ag * nrs2;
;                         const f32x2 dd = (f32x2){__builtin_amdgcn_exp2f(ne.x), __builtin_amdgcn_exp2f(ne.y)} + 1.0f;
;                         const f32x2 rr = (f32x2){__builtin_amdgcn_rcpf(dd.x), __builtin_amdgcn_rcpf(dd.y)};
;                         const f32x2 oo = (g * rr) * up;
;                         wv[n * 2 + hp] = cvt_pk_bf16(oo.x, oo.y);
;                     }
;                 u32x4 w; w.x = wv[0]; w.y = wv[1]; w.z = wv[2]; w.w = wv[3];
;                 __builtin_nontemporal_store(w, (u32x4*)(O + (size_t)row * FF + col0));
	v_pk_mul_f32 v[34:35], v[38:39], v[34:35]
	v_pk_mul_f32 v[38:39], v[38:39], v[170:171] op_sel_hi:[1,0]
	v_exp_f32_e32 v36, v36
	v_exp_f32_e32 v37, v37
	v_exp_f32_e32 v38, v38
	v_exp_f32_e32 v39, v39
	v_pk_fma_f32 v[36:37], v[36:37], v[172:173], v[172:173] op_sel_hi:[1,0,0]
	v_pk_fma_f32 v[38:39], v[38:39], v[172:173], v[172:173] op_sel_hi:[1,0,0]
	v_rcp_f32_e32 v36, v36
	v_rcp_f32_e32 v37, v37
	v_rcp_f32_e32 v38, v38
	v_rcp_f32_e32 v39, v39
	v_pk_mul_f32 v[32:33], v[32:33], v[36:37]
	v_pk_mul_f32 v[34:35], v[34:35], v[38:39]
	v_cvt_pk_bf16_f32 v46, v32, v33
	v_cvt_pk_bf16_f32 v47, v34, v35
	global_store_dwordx4 v[174:175], v[44:47], off nt
	v_mul_f32_e32 v170, 0xbfb8aa3b, v148
	v_mul_f32_e32 v172, v148, v148
	v_add_u32_e32 v167, 160, v166
	v_rcp_f32_e32 v172, v172
	v_mad_i64_i32 v[174:175], s[4:5], v167, s6, v[186:187]
	v_lshl_add_u64 v[174:175], v[174:175], 0, v[188:189]
	v_pk_mul_f32 v[24:25], v[28:29], v[24:25]
	v_pk_mul_f32 v[28:29], v[28:29], v[170:171] op_sel_hi:[1,0]
	v_pk_mul_f32 v[26:27], v[30:31], v[26:27]
	v_pk_mul_f32 v[30:31], v[30:31], v[170:171] op_sel_hi:[1,0]
	v_exp_f32_e32 v28, v28
	v_exp_f32_e32 v29, v29
	v_exp_f32_e32 v30, v30
	v_exp_f32_e32 v31, v31
	v_pk_fma_f32 v[28:29], v[28:29], v[172:173], v[172:173] op_sel_hi:[1,0,0]
	v_pk_fma_f32 v[30:31], v[30:31], v[172:173], v[172:173] op_sel_hi:[1,0,0]
	v_rcp_f32_e32 v28, v28
	v_rcp_f32_e32 v29, v29
	v_rcp_f32_e32 v30, v30
	v_rcp_f32_e32 v31, v31
	v_pk_mul_f32 v[24:25], v[24:25], v[28:29]
	v_pk_mul_f32 v[26:27], v[26:27], v[30:31]
	v_cvt_pk_bf16_f32 v28, v24, v25
	v_cvt_pk_bf16_f32 v29, v26, v27
	v_pk_mul_f32 v[16:17], v[20:21], v[16:17]
	v_pk_mul_f32 v[20:21], v[20:21], v[170:171] op_sel_hi:[1,0]
	v_pk_mul_f32 v[18:19], v[22:23], v[18:19]
	v_pk_mul_f32 v[22:23], v[22:23], v[170:171] op_sel_hi:[1,0]
	v_exp_f32_e32 v20, v20
	v_exp_f32_e32 v21, v21
	v_exp_f32_e32 v22, v22
	v_exp_f32_e32 v23, v23
	v_pk_fma_f32 v[20:21], v[20:21], v[172:173], v[172:173] op_sel_hi:[1,0,0]
	v_pk_fma_f32 v[22:23], v[22:23], v[172:173], v[172:173] op_sel_hi:[1,0,0]
	v_rcp_f32_e32 v20, v20
	v_rcp_f32_e32 v21, v21
	v_rcp_f32_e32 v22, v22
	v_rcp_f32_e32 v23, v23
	v_pk_mul_f32 v[16:17], v[16:17], v[20:21]
	v_pk_mul_f32 v[18:19], v[18:19], v[22:23]
	v_cvt_pk_bf16_f32 v30, v16, v17
	v_cvt_pk_bf16_f32 v31, v18, v19
	global_store_dwordx4 v[174:175], v[28:31], off nt
	v_mul_f32_e32 v170, 0xbfb8aa3b, v149
	v_mul_f32_e32 v172, v149, v149
	v_add_u32_e32 v167, 176, v166
	v_rcp_f32_e32 v172, v172
	v_mad_i64_i32 v[174:175], s[4:5], v167, s6, v[186:187]
	v_lshl_add_u64 v[174:175], v[174:175], 0, v[188:189]
	v_pk_mul_f32 v[8:9], v[12:13], v[8:9]
	v_pk_mul_f32 v[12:13], v[12:13], v[170:171] op_sel_hi:[1,0]
	v_pk_mul_f32 v[10:11], v[14:15], v[10:11]
	v_pk_mul_f32 v[14:15], v[14:15], v[170:171] op_sel_hi:[1,0]
	v_exp_f32_e32 v12, v12
	v_exp_f32_e32 v13, v13
	v_exp_f32_e32 v14, v14
	v_exp_f32_e32 v15, v15
	v_pk_fma_f32 v[12:13], v[12:13], v[172:173], v[172:173] op_sel_hi:[1,0,0]
	v_pk_fma_f32 v[14:15], v[14:15], v[172:173], v[172:173] op_sel_hi:[1,0,0]
	v_rcp_f32_e32 v12, v12
	v_rcp_f32_e32 v13, v13
	v_rcp_f32_e32 v14, v14
	v_rcp_f32_e32 v15, v15
	v_pk_mul_f32 v[8:9], v[8:9], v[12:13]
	v_pk_mul_f32 v[10:11], v[10:11], v[14:15]
	v_cvt_pk_bf16_f32 v12, v8, v9
	v_cvt_pk_bf16_f32 v13, v10, v11
	v_pk_mul_f32 v[0:1], v[4:5], v[0:1]
	v_pk_mul_f32 v[4:5], v[4:5], v[170:171] op_sel_hi:[1,0]
	v_pk_mul_f32 v[2:3], v[6:7], v[2:3]
	v_pk_mul_f32 v[6:7], v[6:7], v[170:171] op_sel_hi:[1,0]
	v_exp_f32_e32 v4, v4
	v_exp_f32_e32 v5, v5
	v_exp_f32_e32 v6, v6
	v_exp_f32_e32 v7, v7
	v_pk_fma_f32 v[4:5], v[4:5], v[172:173], v[172:173] op_sel_hi:[1,0,0]
	v_pk_fma_f32 v[6:7], v[6:7], v[172:173], v[172:173] op_sel_hi:[1,0,0]
	v_rcp_f32_e32 v4, v4
	v_rcp_f32_e32 v5, v5
	v_rcp_f32_e32 v6, v6
	v_rcp_f32_e32 v7, v7
	v_pk_mul_f32 v[0:1], v[0:1], v[4:5]
	v_pk_mul_f32 v[2:3], v[2:3], v[6:7]
	v_cvt_pk_bf16_f32 v14, v0, v1
	v_cvt_pk_bf16_f32 v15, v2, v3
	global_store_dwordx4 v[174:175], v[12:15], off nt
	s_and_b64 vcc, exec, s[40:41]
	s_mov_b64 s[4:5], -1
	s_cbranch_vccnz .LBB0_232
	s_waitcnt vmcnt(8)
	v_add_f32_e32 v0, v60, v61
	v_add_f32_e32 v1, v62, v63
	v_add_f32_e32 v0, v0, v1
	v_add_f32_e32 v1, v56, v57
	v_add_f32_e32 v2, v58, v59
	v_add_f32_e32 v1, v1, v2
	v_add_f32_e32 v0, v1, v0
	ds_bpermute_b32 v1, v159, v0
	s_and_saveexec_b64 s[4:5], s[38:39]
	s_cbranch_execz .LBB0_244
	s_waitcnt lgkmcnt(0)
	v_add_f32_e32 v0, v0, v1
	v_fmamk_f32 v0, v0, 0x3a800000, v222
	v_cmp_gt_f32_e32 vcc, s7, v0
	v_mul_f32_e32 v1, 0x4b800000, v0
	s_xor_b32 s25, s25, 0x400
	v_cndmask_b32_e32 v0, v0, v1, vcc
	v_rsq_f32_e32 v0, v0
	s_nop 0
	v_mul_f32_e32 v1, 0x45800000, v0
	v_cndmask_b32_e32 v0, v0, v1, vcc
	v_add_u32_e32 v1, s25, v162
	ds_write_b32 v1, v0
